# batched+coalesced RMW epilogues (P7,P10), LDS-DMA coalesced weight stream in 16-row tail GEMMs (P2,P9,P6,P7), next-unit q-row L2 prefetch
# speedup vs baseline: 1.0492x; 1.0106x over previous
.LBB0_222:
	v_add_u32_e32 v32, s36, v40
	v_ashrrev_i32_e32 v33, 31, v32
	v_lshlrev_b64 v[32:33], 12, v[32:33]
	v_lshl_add_u64 v[48:49], v[36:37], 0, v[32:33]
	s_nop 0
	v_readfirstlane_b32 s100, v48
	v_readfirstlane_b32 s101, v49
	v_and_b32_e32 v132, 63, v171
	v_lshrrev_b32_e32 v133, 5, v132
	v_and_b32_e32 v134, 31, v132
	v_and_b32_e32 v135, 15, v132
	v_lshrrev_b32_e32 v136, 4, v132
	v_lshrrev_b32_e32 v137, 6, v171
	v_lshlrev_b32_e32 v137, 13, v137
	v_add_u32_e32 v137, 0x2000, v137
	s_nop 1
	v_readfirstlane_b32 s99, v137
	v_lshl_add_u32 v137, v135, 9, v137
	v_add_u32_e32 v138, 0, v133
	v_xor_b32_e32 v139, v134, v138
	v_mul_u32_u24_e32 v138, 0x1000, v138
	v_lshl_add_u32 v140, v139, 4, v138
	v_add_u32_e32 v138, 2, v133
	v_xor_b32_e32 v139, v134, v138
	v_mul_u32_u24_e32 v138, 0x1000, v138
	v_lshl_add_u32 v141, v139, 4, v138
	v_add_u32_e32 v138, 4, v133
	v_xor_b32_e32 v139, v134, v138
	v_mul_u32_u24_e32 v138, 0x1000, v138
	v_lshl_add_u32 v142, v139, 4, v138
	v_add_u32_e32 v138, 6, v133
	v_xor_b32_e32 v139, v134, v138
	v_mul_u32_u24_e32 v138, 0x1000, v138
	v_lshl_add_u32 v143, v139, 4, v138
	v_add_u32_e32 v138, 8, v133
	v_xor_b32_e32 v139, v134, v138
	v_mul_u32_u24_e32 v138, 0x1000, v138
	v_lshl_add_u32 v144, v139, 4, v138
	v_add_u32_e32 v138, 10, v133
	v_xor_b32_e32 v139, v134, v138
	v_mul_u32_u24_e32 v138, 0x1000, v138
	v_lshl_add_u32 v145, v139, 4, v138
	v_add_u32_e32 v138, 12, v133
	v_xor_b32_e32 v139, v134, v138
	v_mul_u32_u24_e32 v138, 0x1000, v138
	v_lshl_add_u32 v146, v139, 4, v138
	v_add_u32_e32 v138, 14, v133
	v_xor_b32_e32 v139, v134, v138
	v_mul_u32_u24_e32 v138, 0x1000, v138
	v_lshl_add_u32 v147, v139, 4, v138
	v_add_u32_e32 v138, 0, v136
	v_xor_b32_e32 v138, v138, v135
	v_lshl_add_u32 v148, v138, 4, v137
	v_add_u32_e32 v138, 4, v136
	v_xor_b32_e32 v138, v138, v135
	v_lshl_add_u32 v149, v138, 4, v137
	v_add_u32_e32 v138, 8, v136
	v_xor_b32_e32 v138, v138, v135
	v_lshl_add_u32 v150, v138, 4, v137
	v_add_u32_e32 v138, 12, v136
	v_xor_b32_e32 v138, v138, v135
	v_lshl_add_u32 v151, v138, 4, v137
	v_add_u32_e32 v138, 16, v136
	v_xor_b32_e32 v138, v138, v135
	v_lshl_add_u32 v152, v138, 4, v137
	v_add_u32_e32 v138, 20, v136
	v_xor_b32_e32 v138, v138, v135
	v_lshl_add_u32 v153, v138, 4, v137
	v_add_u32_e32 v138, 24, v136
	v_xor_b32_e32 v138, v138, v135
	v_lshl_add_u32 v154, v138, 4, v137
	v_add_u32_e32 v138, 28, v136
	v_xor_b32_e32 v138, v138, v135
	v_lshl_add_u32 v155, v138, 4, v137
	s_mov_b32 m0, s99
	s_nop 0
	global_load_lds_dwordx4 v140, s[100:101]
	s_add_u32 s99, s99, 0x400
	s_mov_b32 m0, s99
	s_nop 0
	global_load_lds_dwordx4 v141, s[100:101]
	s_add_u32 s99, s99, 0x400
	s_mov_b32 m0, s99
	s_nop 0
	global_load_lds_dwordx4 v142, s[100:101]
	s_add_u32 s99, s99, 0x400
	s_mov_b32 m0, s99
	s_nop 0
	global_load_lds_dwordx4 v143, s[100:101]
	s_add_u32 s99, s99, 0x400
	s_mov_b32 m0, s99
	s_nop 0
	global_load_lds_dwordx4 v144, s[100:101]
	s_add_u32 s99, s99, 0x400
	s_mov_b32 m0, s99
	s_nop 0
	global_load_lds_dwordx4 v145, s[100:101]
	s_add_u32 s99, s99, 0x400
	s_mov_b32 m0, s99
	s_nop 0
	global_load_lds_dwordx4 v146, s[100:101]
	s_add_u32 s99, s99, 0x400
	s_mov_b32 m0, s99
	s_nop 0
	global_load_lds_dwordx4 v147, s[100:101]
	s_waitcnt vmcnt(0)
	ds_read_b128 v[100:103], v148
	ds_read_b128 v[104:107], v149
	ds_read_b128 v[108:111], v150
	ds_read_b128 v[112:115], v151
	ds_read_b128 v[116:119], v152
	ds_read_b128 v[120:123], v153
	ds_read_b128 v[124:127], v154
	ds_read_b128 v[128:131], v155
	s_waitcnt lgkmcnt(7)
	v_mfma_f32_16x16x32_bf16 v[32:35], v[100:103], v[24:27], 0
	s_waitcnt lgkmcnt(6)
	v_mfma_f32_16x16x32_bf16 v[32:35], v[104:107], v[0:3], v[32:35]
	s_waitcnt lgkmcnt(5)
	v_mfma_f32_16x16x32_bf16 v[32:35], v[108:111], v[4:7], v[32:35]
	s_waitcnt lgkmcnt(4)
	v_mfma_f32_16x16x32_bf16 v[32:35], v[112:115], v[8:11], v[32:35]
	s_waitcnt lgkmcnt(3)
	v_mfma_f32_16x16x32_bf16 v[32:35], v[116:119], v[12:15], v[32:35]
	s_waitcnt lgkmcnt(2)
	v_mfma_f32_16x16x32_bf16 v[32:35], v[120:123], v[16:19], v[32:35]
	s_waitcnt lgkmcnt(1)
	v_mfma_f32_16x16x32_bf16 v[32:35], v[124:127], v[20:23], v[32:35]
	s_waitcnt lgkmcnt(0)
	v_mfma_f32_16x16x32_bf16 v[32:35], v[128:131], v[28:31], v[32:35]
	s_nop 7
	ds_write_b128 v41, v[32:35]
	s_waitcnt lgkmcnt(0)
	s_barrier
	s_and_saveexec_b64 s[0:1], vcc
	s_cbranch_execz .LBB0_221
	ds_read_b128 v[44:47], v41 offset:1024
	ds_read_b128 v[48:51], v41 offset:2048
	ds_read_b128 v[52:55], v41 offset:3072
	ds_read_b128 v[56:59], v41 offset:4096
	s_waitcnt lgkmcnt(3)
	v_pk_add_f32 v[34:35], v[34:35], v[46:47]
	v_pk_add_f32 v[32:33], v[32:33], v[44:45]
	s_waitcnt lgkmcnt(2)
	v_pk_add_f32 v[34:35], v[34:35], v[50:51]
	v_pk_add_f32 v[32:33], v[32:33], v[48:49]
	s_waitcnt lgkmcnt(1)
	v_pk_add_f32 v[44:45], v[34:35], v[54:55]
	v_pk_add_f32 v[48:49], v[32:33], v[52:53]
	ds_read_b128 v[32:35], v41 offset:5120
	s_waitcnt lgkmcnt(1)
	v_pk_add_f32 v[52:53], v[44:45], v[58:59]
	ds_read_b128 v[44:47], v41 offset:6144
	v_pk_add_f32 v[54:55], v[48:49], v[56:57]
	ds_read_b128 v[48:51], v41 offset:7168
	s_waitcnt lgkmcnt(2)
	v_pk_add_f32 v[34:35], v[52:53], v[34:35]
	v_pk_add_f32 v[32:33], v[54:55], v[32:33]
	s_waitcnt lgkmcnt(1)
	v_pk_add_f32 v[34:35], v[34:35], v[46:47]
	v_pk_add_f32 v[32:33], v[32:33], v[44:45]
	v_add_u32_e32 v44, s36, v42
	s_waitcnt lgkmcnt(0)
	v_pk_add_f32 v[34:35], v[34:35], v[50:51]
	v_pk_add_f32 v[32:33], v[32:33], v[48:49]
	v_ashrrev_i32_e32 v45, 31, v44
	v_cvt_pk_bf16_f32 v32, v32, v33
	v_cvt_pk_bf16_f32 v33, v34, v35
	v_lshl_add_u64 v[34:35], v[44:45], 1, v[38:39]
	global_store_dwordx2 v[34:35], v[32:33], off
	s_branch .LBB0_221

.LBB0_439:
	s_add_i32 s36, s81, 1
	s_lshr_b32 s36, s36, 1
	v_mov_b32_e32 v0, s81
	v_mov_b32_e32 v1, s36
	s_lshl_b32 s36, s36, 2
	v_or_b32_e32 v160, s38, v185
	v_cndmask_b32_e64 v0, v0, v1, s[40:41]
	v_mov_b32_e32 v1, s36
	v_cmp_lt_i32_e32 vcc, s16, v160
	v_mov_b32_e32 v3, 0
	v_cndmask_b32_e64 v5, v1, 0, s[40:41]
	v_lshlrev_b32_e32 v6, 2, v0
	s_mov_b64 s[42:43], -1
	v_lshlrev_b32_e32 v162, 2, v172
	v_mov_b32_e32 v4, 0
	s_waitcnt lgkmcnt(0)
	s_barrier
	s_cmp_lg_u32 s76, 0
	s_cbranch_scc1 .Lpf_skip
	v_readfirstlane_b32 s98, v196
	s_sub_i32 s98, 0x803, s98
	s_max_i32 s98, s98, 0
	s_lshl_b32 s98, s98, 2
	v_lshrrev_b32_e32 v253, 4, v172
	v_and_b32_e32 v254, 15, v172
	v_add_u32_e32 v253, s98, v253
	v_lshlrev_b32_e32 v253, 14, v253
	v_lshl_add_u32 v253, v254, 7, v253
	v_add_u32_e32 v253, 0x1200, v253
	global_load_dword v255, v253, s[50:51]
.Lpf_skip:
	s_and_saveexec_b64 s[38:39], vcc
	s_cbranch_execz .LBB0_441
	v_lshl_add_u32 v0, v172, 6, v187
	ds_read_b128 v[8:11], v0
	ds_read_b128 v[12:15], v0 offset:16
	s_waitcnt vmcnt(31)
	ds_read_b128 v[16:19], v0 offset:32
	s_waitcnt vmcnt(30)
	ds_read_b128 v[20:23], v0 offset:48
	s_waitcnt vmcnt(10)
	v_add_u32_e32 v35, 4, v162
	s_waitcnt lgkmcnt(3)
	v_add_u32_sdwa v0, v8, v8 dst_sel:DWORD dst_unused:UNUSED_PAD src0_sel:WORD_1 src1_sel:WORD_0
	v_and_b32_e32 v1, 0xffff, v9
	v_lshrrev_b32_e32 v2, 16, v9
	v_add3_u32 v0, v2, v0, v1
	v_and_b32_e32 v4, 0xffff, v10
	v_lshrrev_b32_e32 v7, 16, v10
	v_add3_u32 v0, v7, v0, v4
	v_and_b32_e32 v9, 0xffff, v11
	v_lshrrev_b32_e32 v10, 16, v11
	v_add3_u32 v0, v10, v0, v9
	s_waitcnt lgkmcnt(2)
	v_and_b32_e32 v11, 0xffff, v12
	v_lshrrev_b32_e32 v12, 16, v12
	v_add3_u32 v0, v12, v0, v11
	v_and_b32_e32 v24, 0xffff, v13
	v_lshrrev_b32_e32 v13, 16, v13
	v_add3_u32 v0, v13, v0, v24
	v_and_b32_e32 v25, 0xffff, v14
	v_lshrrev_b32_e32 v14, 16, v14
	v_add3_u32 v0, v14, v0, v25
	v_and_b32_e32 v26, 0xffff, v15
	v_lshrrev_b32_e32 v15, 16, v15
	v_add3_u32 v0, v15, v0, v26
	s_waitcnt lgkmcnt(1)
	v_and_b32_e32 v27, 0xffff, v16
	v_lshrrev_b32_e32 v16, 16, v16
	v_add3_u32 v0, v16, v0, v27
	v_and_b32_e32 v28, 0xffff, v17
	v_lshrrev_b32_e32 v17, 16, v17
	v_add3_u32 v0, v17, v0, v28
	v_and_b32_e32 v29, 0xffff, v18
	v_lshrrev_b32_e32 v18, 16, v18
	v_add3_u32 v0, v18, v0, v29
	v_and_b32_e32 v30, 0xffff, v19
	v_lshrrev_b32_e32 v19, 16, v19
	v_add3_u32 v0, v19, v0, v30
	s_waitcnt lgkmcnt(0)
	v_and_b32_e32 v31, 0xffff, v20
	v_lshrrev_b32_e32 v20, 16, v20
	v_add3_u32 v0, v20, v0, v31
	v_and_b32_e32 v32, 0xffff, v21
	v_lshrrev_b32_e32 v21, 16, v21
	v_add3_u32 v0, v21, v0, v32
	v_and_b32_e32 v33, 0xffff, v22
	v_lshrrev_b32_e32 v22, 16, v22
	v_add3_u32 v0, v22, v0, v33
	v_and_b32_e32 v34, 0xffff, v23
	v_lshrrev_b32_e32 v23, 16, v23
	v_add3_u32 v0, v23, v0, v34
	v_and_b32_e32 v35, 0xfc, v35
	ds_bpermute_b32 v35, v35, v0
	v_cmp_gt_i32_e64 s[44:45], 63, v172
	v_add_u32_e32 v36, 8, v162
	v_and_b32_e32 v36, 0xfc, v36
	s_movk_i32 s15, 0x80
	s_waitcnt lgkmcnt(0)
	v_cndmask_b32_e64 v35, 0, v35, s[44:45]
	v_add_u32_e32 v35, v35, v0
	ds_bpermute_b32 v36, v36, v35
	v_cmp_gt_i32_e64 s[44:45], 62, v172
	v_cmp_gt_i32_e64 s[46:47], 32, v172
	s_movk_i32 s16, 0x100
	s_waitcnt lgkmcnt(0)
	v_cndmask_b32_e64 v36, 0, v36, s[44:45]
	v_add_u32_e32 v35, v36, v35
	v_add_u32_e32 v36, 16, v162
	v_and_b32_e32 v36, 0xfc, v36
	ds_bpermute_b32 v36, v36, v35
	v_cmp_gt_i32_e64 s[44:45], 60, v172
	s_waitcnt lgkmcnt(0)
	s_nop 0
	v_cndmask_b32_e64 v36, 0, v36, s[44:45]
	v_add_u32_e32 v35, v36, v35
	v_add_u32_e32 v36, 32, v162
	v_and_b32_e32 v36, 0xfc, v36
	ds_bpermute_b32 v36, v36, v35
	v_cmp_gt_i32_e64 s[44:45], 56, v172
	s_waitcnt lgkmcnt(0)
	s_nop 0
	v_cndmask_b32_e64 v36, 0, v36, s[44:45]
	v_add_u32_e32 v35, v36, v35
	v_add_u32_e32 v36, 64, v162
	v_and_b32_e32 v36, 0xfc, v36
	ds_bpermute_b32 v36, v36, v35
	v_cmp_gt_i32_e64 s[44:45], 48, v172
	s_waitcnt lgkmcnt(0)
	s_nop 0
	v_cndmask_b32_e64 v36, 0, v36, s[44:45]
	v_add_u32_e32 v35, v36, v35
	v_bitop3_b32 v36, v162, s15, v182 bitop3:0x6c
	ds_bpermute_b32 v36, v36, v35
	s_movk_i32 s15, 0xff
	v_cmp_ge_u32_e64 s[44:45], v5, v6
	s_waitcnt lgkmcnt(0)
	v_cndmask_b32_e64 v36, 0, v36, s[46:47]
	v_add_u32_e32 v35, v36, v35
	v_sub_u32_e32 v0, v35, v0
	v_add_u32_e32 v0, v23, v0
	v_cmp_lt_i32_e64 s[46:47], s15, v35
	v_add_u32_e32 v23, v34, v0
	s_bcnt1_i32_b64 s42, s[46:47]
	v_cmp_lt_i32_e64 s[46:47], s15, v23
	v_add_u32_e32 v22, v22, v23
	s_add_i32 s42, s42, -1
	v_cndmask_b32_e64 v34, -1, 30, s[46:47]
	v_cmp_gt_i32_e64 s[46:47], s16, v0
	s_movk_i32 s16, 0xff
	s_nop 0
	v_cndmask_b32_e64 v0, 31, v34, s[46:47]
	v_cmp_lt_i32_e64 s[46:47], s15, v22
	v_cmp_gt_i32_e64 s[48:49], 0, v0
	s_and_b64 s[36:37], s[46:47], s[48:49]
	v_cndmask_b32_e64 v0, v0, 29, s[36:37]
	v_add_u32_e32 v22, v33, v22
	v_cmp_lt_i32_e64 s[46:47], s15, v22
	v_cmp_gt_i32_e64 s[48:49], 0, v0
	s_and_b64 s[36:37], s[46:47], s[48:49]
	v_cndmask_b32_e64 v0, v0, 28, s[36:37]
	v_add_u32_e32 v21, v21, v22
	v_cmp_lt_i32_e64 s[46:47], s15, v21
	v_cmp_gt_i32_e64 s[48:49], 0, v0
	s_and_b64 s[36:37], s[46:47], s[48:49]
	v_cndmask_b32_e64 v0, v0, 27, s[36:37]
	v_add_u32_e32 v21, v32, v21
	v_cmp_lt_i32_e64 s[46:47], s15, v21
	v_cmp_gt_i32_e64 s[48:49], 0, v0
	s_and_b64 s[36:37], s[46:47], s[48:49]
	v_cndmask_b32_e64 v0, v0, 26, s[36:37]
	v_add_u32_e32 v20, v20, v21
	v_cmp_lt_i32_e64 s[46:47], s15, v20
	v_cmp_gt_i32_e64 s[48:49], 0, v0
	s_and_b64 s[36:37], s[46:47], s[48:49]
	v_cndmask_b32_e64 v0, v0, 25, s[36:37]
	v_add_u32_e32 v20, v31, v20
	v_cmp_lt_i32_e64 s[46:47], s15, v20
	v_cmp_gt_i32_e64 s[48:49], 0, v0
	s_and_b64 s[36:37], s[46:47], s[48:49]
	v_cndmask_b32_e64 v0, v0, 24, s[36:37]
	v_add_u32_e32 v19, v19, v20
	v_cmp_lt_i32_e64 s[46:47], s15, v19
	v_cmp_gt_i32_e64 s[48:49], 0, v0
	s_and_b64 s[36:37], s[46:47], s[48:49]
	v_cndmask_b32_e64 v0, v0, 23, s[36:37]
	v_add_u32_e32 v19, v30, v19
	v_cmp_lt_i32_e64 s[46:47], s15, v19
	v_cmp_gt_i32_e64 s[48:49], 0, v0
	s_and_b64 s[36:37], s[46:47], s[48:49]
	v_cndmask_b32_e64 v0, v0, 22, s[36:37]
	v_add_u32_e32 v18, v18, v19
	v_cmp_lt_i32_e64 s[46:47], s15, v18
	v_cmp_gt_i32_e64 s[48:49], 0, v0
	s_and_b64 s[36:37], s[46:47], s[48:49]
	v_cndmask_b32_e64 v0, v0, 21, s[36:37]
	v_add_u32_e32 v18, v29, v18
	v_cmp_lt_i32_e64 s[46:47], s15, v18
	v_cmp_gt_i32_e64 s[48:49], 0, v0
	s_and_b64 s[36:37], s[46:47], s[48:49]
	v_cndmask_b32_e64 v0, v0, 20, s[36:37]
	v_add_u32_e32 v17, v17, v18
	v_cmp_lt_i32_e64 s[46:47], s15, v17
	v_cmp_gt_i32_e64 s[48:49], 0, v0
	s_and_b64 s[36:37], s[46:47], s[48:49]
	v_cndmask_b32_e64 v0, v0, 19, s[36:37]
	v_add_u32_e32 v17, v28, v17
	v_cmp_lt_i32_e64 s[46:47], s15, v17
	v_cmp_gt_i32_e64 s[48:49], 0, v0
	s_and_b64 s[36:37], s[46:47], s[48:49]
	v_cndmask_b32_e64 v0, v0, 18, s[36:37]
	v_add_u32_e32 v16, v16, v17
	v_cmp_lt_i32_e64 s[46:47], s15, v16
	v_cmp_gt_i32_e64 s[48:49], 0, v0
	s_and_b64 s[36:37], s[46:47], s[48:49]
	v_cndmask_b32_e64 v0, v0, 17, s[36:37]
	v_add_u32_e32 v16, v27, v16
	v_cmp_lt_i32_e64 s[46:47], s15, v16
	v_cmp_gt_i32_e64 s[48:49], 0, v0
	s_and_b64 s[36:37], s[46:47], s[48:49]
	v_cndmask_b32_e64 v0, v0, 16, s[36:37]
	v_add_u32_e32 v15, v15, v16
	v_cmp_lt_i32_e64 s[46:47], s15, v15
	v_cmp_gt_i32_e64 s[48:49], 0, v0
	s_and_b64 s[36:37], s[46:47], s[48:49]
	v_cndmask_b32_e64 v0, v0, 15, s[36:37]
	v_add_u32_e32 v15, v26, v15
	v_cmp_lt_i32_e64 s[46:47], s15, v15
	v_cmp_gt_i32_e64 s[48:49], 0, v0
	s_and_b64 s[36:37], s[46:47], s[48:49]
	v_cndmask_b32_e64 v0, v0, 14, s[36:37]
	v_add_u32_e32 v14, v14, v15
	v_cmp_lt_i32_e64 s[46:47], s15, v14
	v_cmp_gt_i32_e64 s[48:49], 0, v0
	s_and_b64 s[36:37], s[46:47], s[48:49]
	v_cndmask_b32_e64 v0, v0, 13, s[36:37]
	v_add_u32_e32 v14, v25, v14
	v_cmp_lt_i32_e64 s[46:47], s15, v14
	v_cmp_gt_i32_e64 s[48:49], 0, v0
	s_and_b64 s[36:37], s[46:47], s[48:49]
	v_cndmask_b32_e64 v0, v0, 12, s[36:37]
	v_add_u32_e32 v13, v13, v14
	v_cmp_lt_i32_e64 s[46:47], s15, v13
	v_cmp_gt_i32_e64 s[48:49], 0, v0
	s_and_b64 s[36:37], s[46:47], s[48:49]
	v_cndmask_b32_e64 v0, v0, 11, s[36:37]
	v_add_u32_e32 v13, v24, v13
	v_cmp_lt_i32_e64 s[46:47], s15, v13
	v_cmp_gt_i32_e64 s[48:49], 0, v0
	s_and_b64 s[36:37], s[46:47], s[48:49]
	v_cndmask_b32_e64 v0, v0, 10, s[36:37]
	v_add_u32_e32 v12, v12, v13
	v_cmp_lt_i32_e64 s[46:47], s15, v12
	v_cmp_gt_i32_e64 s[48:49], 0, v0
	s_and_b64 s[36:37], s[46:47], s[48:49]
	v_cndmask_b32_e64 v0, v0, 9, s[36:37]
	v_add_u32_e32 v11, v11, v12
	v_cmp_lt_i32_e64 s[46:47], s15, v11
	v_cmp_gt_i32_e64 s[48:49], 0, v0
	s_and_b64 s[36:37], s[46:47], s[48:49]
	v_cndmask_b32_e64 v0, v0, 8, s[36:37]
	v_add_u32_e32 v10, v10, v11
	v_cmp_lt_i32_e64 s[46:47], s15, v10
	v_cmp_gt_i32_e64 s[48:49], 0, v0
	s_and_b64 s[36:37], s[46:47], s[48:49]
	v_cndmask_b32_e64 v0, v0, 7, s[36:37]
	v_add_u32_e32 v9, v9, v10
	v_cmp_lt_i32_e64 s[46:47], s15, v9
	v_cmp_gt_i32_e64 s[48:49], 0, v0
	s_and_b64 s[36:37], s[46:47], s[48:49]
	v_cndmask_b32_e64 v0, v0, 6, s[36:37]
	v_add_u32_e32 v7, v7, v9
	v_cmp_lt_i32_e64 s[46:47], s15, v7
	v_cmp_gt_i32_e64 s[48:49], 0, v0
	s_and_b64 s[36:37], s[46:47], s[48:49]
	v_cndmask_b32_e64 v0, v0, 5, s[36:37]
	v_add_u32_e32 v4, v4, v7
	v_cmp_lt_i32_e64 s[46:47], s15, v4
	v_cmp_gt_i32_e64 s[48:49], 0, v0
	s_and_b64 s[36:37], s[46:47], s[48:49]
	v_cndmask_b32_e64 v0, v0, 4, s[36:37]
	v_add_u32_e32 v2, v2, v4
	v_cmp_lt_i32_e64 s[46:47], s15, v2
	v_cmp_gt_i32_e64 s[48:49], 0, v0
	s_and_b64 s[36:37], s[46:47], s[48:49]
	v_cndmask_b32_e64 v0, v0, 3, s[36:37]
	v_add_u32_e32 v1, v1, v2
	v_cmp_lt_i32_e64 s[46:47], s15, v1
	v_cmp_gt_i32_e64 s[48:49], 0, v0
	s_and_b64 s[36:37], s[46:47], s[48:49]
	v_cndmask_b32_e64 v0, v0, 2, s[36:37]
	v_add_u32_sdwa v1, v8, v1 dst_sel:DWORD dst_unused:UNUSED_PAD src0_sel:WORD_1 src1_sel:DWORD
	v_cmp_lt_i32_e64 s[46:47], s15, v1
	v_cmp_gt_i32_e64 s[48:49], 0, v0
	s_and_b64 s[36:37], s[46:47], s[48:49]
	v_cndmask_b32_e64 v0, v0, 1, s[36:37]
	v_add_u32_sdwa v1, v8, v1 dst_sel:DWORD dst_unused:UNUSED_PAD src0_sel:WORD_0 src1_sel:DWORD
	v_max_i32_e32 v2, 0, v0
	v_cmp_lt_i32_e64 s[46:47], s15, v1
	s_lshl_b32 s37, s42, 26
	s_nop 0
	v_cndmask_b32_e64 v0, v0, v2, s[46:47]
	s_nop 0
	v_readlane_b32 s36, v0, s42
	s_lshl_b32 s36, s36, 21
	s_add_i32 s36, s36, s37
	v_mov_b32_e32 v4, s36
	s_orn2_b64 s[42:43], s[44:45], exec

.LBB0_950:
	v_add_u32_e32 v32, s36, v44
	v_ashrrev_i32_e32 v33, 31, v32
	v_lshlrev_b64 v[32:33], 12, v[32:33]
	v_lshl_add_u64 v[52:53], v[36:37], 0, v[32:33]
	s_nop 0
	v_readfirstlane_b32 s100, v52
	v_readfirstlane_b32 s101, v53
	v_and_b32_e32 v132, 63, v171
	v_lshrrev_b32_e32 v133, 5, v132
	v_and_b32_e32 v134, 31, v132
	v_and_b32_e32 v135, 15, v132
	v_lshrrev_b32_e32 v136, 4, v132
	v_lshrrev_b32_e32 v137, 6, v171
	v_lshlrev_b32_e32 v137, 13, v137
	v_add_u32_e32 v137, 0x2000, v137
	s_nop 1
	v_readfirstlane_b32 s99, v137
	v_lshl_add_u32 v137, v135, 9, v137
	v_add_u32_e32 v138, 0, v133
	v_xor_b32_e32 v139, v134, v138
	v_mul_u32_u24_e32 v138, 0x1000, v138
	v_lshl_add_u32 v140, v139, 4, v138
	v_add_u32_e32 v138, 2, v133
	v_xor_b32_e32 v139, v134, v138
	v_mul_u32_u24_e32 v138, 0x1000, v138
	v_lshl_add_u32 v141, v139, 4, v138
	v_add_u32_e32 v138, 4, v133
	v_xor_b32_e32 v139, v134, v138
	v_mul_u32_u24_e32 v138, 0x1000, v138
	v_lshl_add_u32 v142, v139, 4, v138
	v_add_u32_e32 v138, 6, v133
	v_xor_b32_e32 v139, v134, v138
	v_mul_u32_u24_e32 v138, 0x1000, v138
	v_lshl_add_u32 v143, v139, 4, v138
	v_add_u32_e32 v138, 8, v133
	v_xor_b32_e32 v139, v134, v138
	v_mul_u32_u24_e32 v138, 0x1000, v138
	v_lshl_add_u32 v144, v139, 4, v138
	v_add_u32_e32 v138, 10, v133
	v_xor_b32_e32 v139, v134, v138
	v_mul_u32_u24_e32 v138, 0x1000, v138
	v_lshl_add_u32 v145, v139, 4, v138
	v_add_u32_e32 v138, 12, v133
	v_xor_b32_e32 v139, v134, v138
	v_mul_u32_u24_e32 v138, 0x1000, v138
	v_lshl_add_u32 v146, v139, 4, v138
	v_add_u32_e32 v138, 14, v133
	v_xor_b32_e32 v139, v134, v138
	v_mul_u32_u24_e32 v138, 0x1000, v138
	v_lshl_add_u32 v147, v139, 4, v138
	v_add_u32_e32 v138, 0, v136
	v_xor_b32_e32 v138, v138, v135
	v_lshl_add_u32 v148, v138, 4, v137
	v_add_u32_e32 v138, 4, v136
	v_xor_b32_e32 v138, v138, v135
	v_lshl_add_u32 v149, v138, 4, v137
	v_add_u32_e32 v138, 8, v136
	v_xor_b32_e32 v138, v138, v135
	v_lshl_add_u32 v150, v138, 4, v137
	v_add_u32_e32 v138, 12, v136
	v_xor_b32_e32 v138, v138, v135
	v_lshl_add_u32 v151, v138, 4, v137
	v_add_u32_e32 v138, 16, v136
	v_xor_b32_e32 v138, v138, v135
	v_lshl_add_u32 v152, v138, 4, v137
	v_add_u32_e32 v138, 20, v136
	v_xor_b32_e32 v138, v138, v135
	v_lshl_add_u32 v153, v138, 4, v137
	v_add_u32_e32 v138, 24, v136
	v_xor_b32_e32 v138, v138, v135
	v_lshl_add_u32 v154, v138, 4, v137
	v_add_u32_e32 v138, 28, v136
	v_xor_b32_e32 v138, v138, v135
	v_lshl_add_u32 v155, v138, 4, v137
	s_mov_b32 m0, s99
	s_nop 0
	global_load_lds_dwordx4 v140, s[100:101]
	s_add_u32 s99, s99, 0x400
	s_mov_b32 m0, s99
	s_nop 0
	global_load_lds_dwordx4 v141, s[100:101]
	s_add_u32 s99, s99, 0x400
	s_mov_b32 m0, s99
	s_nop 0
	global_load_lds_dwordx4 v142, s[100:101]
	s_add_u32 s99, s99, 0x400
	s_mov_b32 m0, s99
	s_nop 0
	global_load_lds_dwordx4 v143, s[100:101]
	s_add_u32 s99, s99, 0x400
	s_mov_b32 m0, s99
	s_nop 0
	global_load_lds_dwordx4 v144, s[100:101]
	s_add_u32 s99, s99, 0x400
	s_mov_b32 m0, s99
	s_nop 0
	global_load_lds_dwordx4 v145, s[100:101]
	s_add_u32 s99, s99, 0x400
	s_mov_b32 m0, s99
	s_nop 0
	global_load_lds_dwordx4 v146, s[100:101]
	s_add_u32 s99, s99, 0x400
	s_mov_b32 m0, s99
	s_nop 0
	global_load_lds_dwordx4 v147, s[100:101]
	s_waitcnt vmcnt(0)
	ds_read_b128 v[100:103], v148
	ds_read_b128 v[104:107], v149
	ds_read_b128 v[108:111], v150
	ds_read_b128 v[112:115], v151
	ds_read_b128 v[116:119], v152
	ds_read_b128 v[120:123], v153
	ds_read_b128 v[124:127], v154
	ds_read_b128 v[128:131], v155
	s_waitcnt lgkmcnt(7)
	v_mfma_f32_16x16x32_bf16 v[32:35], v[100:103], v[24:27], 0
	s_waitcnt lgkmcnt(6)
	v_mfma_f32_16x16x32_bf16 v[32:35], v[104:107], v[0:3], v[32:35]
	s_waitcnt lgkmcnt(5)
	v_mfma_f32_16x16x32_bf16 v[32:35], v[108:111], v[4:7], v[32:35]
	s_waitcnt lgkmcnt(4)
	v_mfma_f32_16x16x32_bf16 v[32:35], v[112:115], v[8:11], v[32:35]
	s_waitcnt lgkmcnt(3)
	v_mfma_f32_16x16x32_bf16 v[32:35], v[116:119], v[12:15], v[32:35]
	s_waitcnt lgkmcnt(2)
	v_mfma_f32_16x16x32_bf16 v[32:35], v[120:123], v[16:19], v[32:35]
	s_waitcnt lgkmcnt(1)
	v_mfma_f32_16x16x32_bf16 v[32:35], v[124:127], v[20:23], v[32:35]
	s_waitcnt lgkmcnt(0)
	v_mfma_f32_16x16x32_bf16 v[32:35], v[128:131], v[28:31], v[32:35]
	s_nop 7
	ds_write_b128 v45, v[32:35]
	s_waitcnt lgkmcnt(0)
	s_barrier
	s_and_saveexec_b64 s[0:1], vcc
	s_cbranch_execz .LBB0_949
	ds_read_b128 v[48:51], v45 offset:1024
	s_waitcnt lgkmcnt(0)
	v_pk_add_f32 v[50:51], v[34:35], v[50:51]
	v_pk_add_f32 v[48:49], v[32:33], v[48:49]
	ds_read_b128 v[32:35], v45 offset:2048
	s_waitcnt lgkmcnt(0)
	v_pk_add_f32 v[50:51], v[50:51], v[34:35]
	v_pk_add_f32 v[48:49], v[48:49], v[32:33]
	ds_read_b128 v[32:35], v45 offset:3072
	s_waitcnt lgkmcnt(0)
	v_pk_add_f32 v[50:51], v[50:51], v[34:35]
	v_pk_add_f32 v[48:49], v[48:49], v[32:33]
	ds_read_b128 v[32:35], v45 offset:4096
	s_waitcnt lgkmcnt(0)
	v_pk_add_f32 v[50:51], v[50:51], v[34:35]
	v_pk_add_f32 v[48:49], v[48:49], v[32:33]
	ds_read_b128 v[32:35], v45 offset:5120
	s_waitcnt lgkmcnt(0)
	v_pk_add_f32 v[50:51], v[50:51], v[34:35]
	v_pk_add_f32 v[48:49], v[48:49], v[32:33]
	ds_read_b128 v[32:35], v45 offset:6144
	s_waitcnt lgkmcnt(0)
	v_pk_add_f32 v[34:35], v[50:51], v[34:35]
	v_pk_add_f32 v[52:53], v[48:49], v[32:33]
	ds_read_b128 v[48:51], v45 offset:7168
	s_waitcnt lgkmcnt(0)
	v_pk_add_f32 v[32:33], v[34:35], v[50:51]
	v_pk_add_f32 v[34:35], v[52:53], v[48:49]
	v_add_u32_e32 v48, s36, v46
	v_ashrrev_i32_e32 v49, 31, v48
	v_lshlrev_b64 v[52:53], 1, v[48:49]
	v_lshl_add_u64 v[50:51], v[38:39], 0, v[52:53]
	global_load_dwordx2 v[54:55], v[50:51], off
	v_lshl_add_u64 v[48:49], v[48:49], 2, v[40:41]
	global_load_dwordx4 v[48:51], v[48:49], off
	s_waitcnt vmcnt(1)
	v_lshlrev_b32_e32 v47, 16, v54
	v_mul_f32_e32 v47, 0xbfb8aa3b, v47
	v_exp_f32_e32 v47, v47
	s_nop 0
	v_add_f32_e32 v47, 1.0, v47
	v_rcp_f32_e32 v56, v47
	v_and_b32_e32 v47, 0xffff0000, v54
	v_mul_f32_e32 v47, 0xbfb8aa3b, v47
	v_exp_f32_e32 v47, v47
	s_nop 0
	v_add_f32_e32 v47, 1.0, v47
	v_rcp_f32_e32 v57, v47
	s_waitcnt vmcnt(0)
	v_pk_fma_f32 v[34:35], v[34:35], v[56:57], v[48:49]
	s_nop 0
	v_cvt_pk_bf16_f32 v34, v34, v35
	v_lshlrev_b32_e32 v35, 16, v55
	v_mul_f32_e32 v35, 0xbfb8aa3b, v35
	v_exp_f32_e32 v35, v35
	s_nop 0
	v_add_f32_e32 v35, 1.0, v35
	v_rcp_f32_e32 v48, v35
	v_and_b32_e32 v35, 0xffff0000, v55
	v_mul_f32_e32 v35, 0xbfb8aa3b, v35
	v_exp_f32_e32 v35, v35
	s_nop 0
	v_add_f32_e32 v35, 1.0, v35
	v_rcp_f32_e32 v49, v35
	s_nop 0
	v_pk_fma_f32 v[32:33], v[32:33], v[48:49], v[50:51]
	s_nop 0
	v_cvt_pk_bf16_f32 v35, v32, v33
	v_lshl_add_u64 v[32:33], v[42:43], 0, v[52:53]
	global_store_dwordx2 v[32:33], v[34:35], off
	s_branch .LBB0_949

.LBB0_1006:
	s_or_b64 exec, exec, s[44:45]
	v_or_b32_e32 v128, s38, v143
	v_add_u32_e32 v130, v128, v144
	v_lshlrev_b32_e32 v128, 5, v141
	v_lshlrev_b32_e32 v129, 3, v142
	v_or3_b32 v128, v128, v129, s0
	v_ashrrev_i32_e32 v131, 31, v130
	v_lshlrev_b64 v[132:133], 13, v[130:131]
	v_ashrrev_i32_e32 v129, 31, v128
	v_lshl_add_u64 v[132:133], s[40:41], 0, v[132:133]
	v_lshlrev_b64 v[128:129], 2, v[128:129]
	v_lshl_add_u64 v[140:141], v[132:133], 0, v[128:129]
	v_and_b32_e32 v249, 63, v171
	v_and_b32_e32 v146, 15, v249
	v_lshrrev_b32_e32 v147, 4, v249
	v_lshrrev_b32_e32 v164, 6, v171
	v_mul_u32_u24_e32 v164, 0xe00, v164
	v_add_u32_e32 v164, 0x20000, v164
	v_mul_u32_u24_e32 v165, 0x90, v146
	v_lshl_add_u32 v165, v147, 5, v165
	v_add_u32_e32 v165, v165, v164
	v_lshrrev_b32_e32 v166, 3, v249
	v_mul_u32_u24_e32 v167, 0x90, v166
	v_and_b32_e32 v148, 7, v249
	v_lshl_add_u32 v167, v148, 4, v167
	v_add_u32_e32 v167, v167, v164
	v_sub_u32_e32 v248, v130, v146
	v_add_u32_e32 v248, v248, v166
	v_lshlrev_b32_e32 v248, 13, v248
	v_lshlrev_b32_e32 v149, 5, v147
	v_sub_u32_e32 v149, v128, v149
	v_lshl_add_u32 v149, v148, 4, v149
	v_add_u32_e32 v248, v248, v149
	s_mov_b64 s[100:101], s[40:41]
	global_load_dwordx4 v[184:187], v248, s[100:101]
	global_load_dwordx4 v[192:195], v248, s[100:101] offset:512
	s_add_u32 s100, s40, 0x10000
	s_addc_u32 s101, s41, 0
	global_load_dwordx4 v[188:191], v248, s[100:101]
	global_load_dwordx4 v[196:199], v248, s[100:101] offset:512
	s_add_u32 s100, s40, 0x20000
	s_addc_u32 s101, s41, 0
	global_load_dwordx4 v[200:203], v248, s[100:101]
	global_load_dwordx4 v[208:211], v248, s[100:101] offset:512
	s_add_u32 s100, s40, 0x30000
	s_addc_u32 s101, s41, 0
	global_load_dwordx4 v[204:207], v248, s[100:101]
	global_load_dwordx4 v[212:215], v248, s[100:101] offset:512
	s_add_u32 s100, s40, 0x40000
	s_addc_u32 s101, s41, 0
	global_load_dwordx4 v[216:219], v248, s[100:101]
	global_load_dwordx4 v[224:227], v248, s[100:101] offset:512
	s_add_u32 s100, s40, 0x50000
	s_addc_u32 s101, s41, 0
	global_load_dwordx4 v[220:223], v248, s[100:101]
	global_load_dwordx4 v[228:231], v248, s[100:101] offset:512
	s_add_u32 s100, s40, 0x60000
	s_addc_u32 s101, s41, 0
	global_load_dwordx4 v[232:235], v248, s[100:101]
	global_load_dwordx4 v[240:243], v248, s[100:101] offset:512
	s_add_u32 s100, s40, 0x70000
	s_addc_u32 s101, s41, 0
	global_load_dwordx4 v[236:239], v248, s[100:101]
	global_load_dwordx4 v[244:247], v248, s[100:101] offset:512
	ds_write_b128 v165, v[124:127]
	ds_write_b128 v165, v[120:123] offset:16
	ds_read_b128 v[124:127], v167
	ds_read_b128 v[120:123], v167 offset:1152
	ds_write_b128 v165, v[116:119]
	ds_write_b128 v165, v[112:115] offset:16
	ds_read_b128 v[116:119], v167
	ds_read_b128 v[112:115], v167 offset:1152
	ds_write_b128 v165, v[100:103]
	ds_write_b128 v165, v[96:99] offset:16
	ds_read_b128 v[100:103], v167
	ds_read_b128 v[96:99], v167 offset:1152
	ds_write_b128 v165, v[108:111]
	ds_write_b128 v165, v[104:107] offset:16
	ds_read_b128 v[108:111], v167
	ds_read_b128 v[104:107], v167 offset:1152
	ds_write_b128 v165, v[84:87]
	ds_write_b128 v165, v[80:83] offset:16
	ds_read_b128 v[84:87], v167
	ds_read_b128 v[80:83], v167 offset:1152
	ds_write_b128 v165, v[92:95]
	ds_write_b128 v165, v[88:91] offset:16
	ds_read_b128 v[92:95], v167
	ds_read_b128 v[88:91], v167 offset:1152
	ds_write_b128 v165, v[68:71]
	ds_write_b128 v165, v[64:67] offset:16
	ds_read_b128 v[68:71], v167
	ds_read_b128 v[64:67], v167 offset:1152
	ds_write_b128 v165, v[76:79]
	ds_write_b128 v165, v[72:75] offset:16
	ds_read_b128 v[76:79], v167
	ds_read_b128 v[72:75], v167 offset:1152
	ds_write_b128 v165, v[52:55]
	ds_write_b128 v165, v[48:51] offset:16
	ds_read_b128 v[52:55], v167
	ds_read_b128 v[48:51], v167 offset:1152
	ds_write_b128 v165, v[60:63]
	ds_write_b128 v165, v[56:59] offset:16
	ds_read_b128 v[60:63], v167
	ds_read_b128 v[56:59], v167 offset:1152
	ds_write_b128 v165, v[36:39]
	ds_write_b128 v165, v[32:35] offset:16
	ds_read_b128 v[36:39], v167
	ds_read_b128 v[32:35], v167 offset:1152
	ds_write_b128 v165, v[44:47]
	ds_write_b128 v165, v[40:43] offset:16
	ds_read_b128 v[44:47], v167
	ds_read_b128 v[40:43], v167 offset:1152
	ds_write_b128 v165, v[20:23]
	ds_write_b128 v165, v[16:19] offset:16
	ds_read_b128 v[20:23], v167
	ds_read_b128 v[16:19], v167 offset:1152
	ds_write_b128 v165, v[28:31]
	ds_write_b128 v165, v[24:27] offset:16
	ds_read_b128 v[28:31], v167
	ds_read_b128 v[24:27], v167 offset:1152
	ds_write_b128 v165, v[12:15]
	ds_write_b128 v165, v[8:11] offset:16
	ds_read_b128 v[12:15], v167
	ds_read_b128 v[8:11], v167 offset:1152
	ds_write_b128 v165, v[4:7]
	ds_write_b128 v165, v[0:3] offset:16
	ds_read_b128 v[4:7], v167
	ds_read_b128 v[0:3], v167 offset:1152
	s_waitcnt lgkmcnt(0)
	s_waitcnt vmcnt(8)
	v_pk_add_f32 v[124:125], v[124:125], v[184:185]
	v_pk_add_f32 v[126:127], v[126:127], v[186:187]
	v_pk_add_f32 v[120:121], v[120:121], v[188:189]
	v_pk_add_f32 v[122:123], v[122:123], v[190:191]
	v_pk_add_f32 v[116:117], v[116:117], v[192:193]
	v_pk_add_f32 v[118:119], v[118:119], v[194:195]
	v_pk_add_f32 v[112:113], v[112:113], v[196:197]
	v_pk_add_f32 v[114:115], v[114:115], v[198:199]
	v_pk_add_f32 v[100:101], v[100:101], v[200:201]
	v_pk_add_f32 v[102:103], v[102:103], v[202:203]
	v_pk_add_f32 v[96:97], v[96:97], v[204:205]
	v_pk_add_f32 v[98:99], v[98:99], v[206:207]
	v_pk_add_f32 v[108:109], v[108:109], v[208:209]
	v_pk_add_f32 v[110:111], v[110:111], v[210:211]
	v_pk_add_f32 v[104:105], v[104:105], v[212:213]
	v_pk_add_f32 v[106:107], v[106:107], v[214:215]
	s_add_u32 s100, s40, 0x100000
	s_addc_u32 s101, s41, 0
	global_load_dwordx4 v[184:187], v248, s[100:101]
	global_load_dwordx4 v[192:195], v248, s[100:101] offset:512
	s_add_u32 s100, s40, 0x110000
	s_addc_u32 s101, s41, 0
	global_load_dwordx4 v[188:191], v248, s[100:101]
	global_load_dwordx4 v[196:199], v248, s[100:101] offset:512
	s_add_u32 s100, s40, 0x120000
	s_addc_u32 s101, s41, 0
	global_load_dwordx4 v[200:203], v248, s[100:101]
	global_load_dwordx4 v[208:211], v248, s[100:101] offset:512
	s_add_u32 s100, s40, 0x130000
	s_addc_u32 s101, s41, 0
	global_load_dwordx4 v[204:207], v248, s[100:101]
	global_load_dwordx4 v[212:215], v248, s[100:101] offset:512
	s_mov_b64 s[100:101], s[40:41]
	global_store_dwordx4 v248, v[124:127], s[100:101]
	global_store_dwordx4 v248, v[116:119], s[100:101] offset:512
	s_add_u32 s100, s40, 0x10000
	s_addc_u32 s101, s41, 0
	global_store_dwordx4 v248, v[120:123], s[100:101]
	global_store_dwordx4 v248, v[112:115], s[100:101] offset:512
	s_add_u32 s100, s40, 0x20000
	s_addc_u32 s101, s41, 0
	global_store_dwordx4 v248, v[100:103], s[100:101]
	global_store_dwordx4 v248, v[108:111], s[100:101] offset:512
	s_add_u32 s100, s40, 0x30000
	s_addc_u32 s101, s41, 0
	global_store_dwordx4 v248, v[96:99], s[100:101]
	global_store_dwordx4 v248, v[104:107], s[100:101] offset:512
	s_waitcnt vmcnt(16)
	v_pk_add_f32 v[84:85], v[84:85], v[216:217]
	v_pk_add_f32 v[86:87], v[86:87], v[218:219]
	v_pk_add_f32 v[80:81], v[80:81], v[220:221]
	v_pk_add_f32 v[82:83], v[82:83], v[222:223]
	v_pk_add_f32 v[92:93], v[92:93], v[224:225]
	v_pk_add_f32 v[94:95], v[94:95], v[226:227]
	v_pk_add_f32 v[88:89], v[88:89], v[228:229]
	v_pk_add_f32 v[90:91], v[90:91], v[230:231]
	v_pk_add_f32 v[68:69], v[68:69], v[232:233]
	v_pk_add_f32 v[70:71], v[70:71], v[234:235]
	v_pk_add_f32 v[64:65], v[64:65], v[236:237]
	v_pk_add_f32 v[66:67], v[66:67], v[238:239]
	v_pk_add_f32 v[76:77], v[76:77], v[240:241]
	v_pk_add_f32 v[78:79], v[78:79], v[242:243]
	v_pk_add_f32 v[72:73], v[72:73], v[244:245]
	v_pk_add_f32 v[74:75], v[74:75], v[246:247]
	s_add_u32 s100, s40, 0x140000
	s_addc_u32 s101, s41, 0
	global_load_dwordx4 v[216:219], v248, s[100:101]
	global_load_dwordx4 v[224:227], v248, s[100:101] offset:512
	s_add_u32 s100, s40, 0x150000
	s_addc_u32 s101, s41, 0
	global_load_dwordx4 v[220:223], v248, s[100:101]
	global_load_dwordx4 v[228:231], v248, s[100:101] offset:512
	s_add_u32 s100, s40, 0x160000
	s_addc_u32 s101, s41, 0
	global_load_dwordx4 v[232:235], v248, s[100:101]
	global_load_dwordx4 v[240:243], v248, s[100:101] offset:512
	s_add_u32 s100, s40, 0x170000
	s_addc_u32 s101, s41, 0
	global_load_dwordx4 v[236:239], v248, s[100:101]
	global_load_dwordx4 v[244:247], v248, s[100:101] offset:512
	s_add_u32 s100, s40, 0x40000
	s_addc_u32 s101, s41, 0
	global_store_dwordx4 v248, v[84:87], s[100:101]
	global_store_dwordx4 v248, v[92:95], s[100:101] offset:512
	s_add_u32 s100, s40, 0x50000
	s_addc_u32 s101, s41, 0
	global_store_dwordx4 v248, v[80:83], s[100:101]
	global_store_dwordx4 v248, v[88:91], s[100:101] offset:512
	s_add_u32 s100, s40, 0x60000
	s_addc_u32 s101, s41, 0
	global_store_dwordx4 v248, v[68:71], s[100:101]
	global_store_dwordx4 v248, v[76:79], s[100:101] offset:512
	s_add_u32 s100, s40, 0x70000
	s_addc_u32 s101, s41, 0
	global_store_dwordx4 v248, v[64:67], s[100:101]
	global_store_dwordx4 v248, v[72:75], s[100:101] offset:512
	s_waitcnt vmcnt(24)
	v_pk_add_f32 v[52:53], v[52:53], v[184:185]
	v_pk_add_f32 v[54:55], v[54:55], v[186:187]
	v_pk_add_f32 v[48:49], v[48:49], v[188:189]
	v_pk_add_f32 v[50:51], v[50:51], v[190:191]
	v_pk_add_f32 v[60:61], v[60:61], v[192:193]
	v_pk_add_f32 v[62:63], v[62:63], v[194:195]
	v_pk_add_f32 v[56:57], v[56:57], v[196:197]
	v_pk_add_f32 v[58:59], v[58:59], v[198:199]
	v_pk_add_f32 v[36:37], v[36:37], v[200:201]
	v_pk_add_f32 v[38:39], v[38:39], v[202:203]
	v_pk_add_f32 v[32:33], v[32:33], v[204:205]
	v_pk_add_f32 v[34:35], v[34:35], v[206:207]
	v_pk_add_f32 v[44:45], v[44:45], v[208:209]
	v_pk_add_f32 v[46:47], v[46:47], v[210:211]
	v_pk_add_f32 v[40:41], v[40:41], v[212:213]
	v_pk_add_f32 v[42:43], v[42:43], v[214:215]
	s_add_u32 s100, s40, 0x100000
	s_addc_u32 s101, s41, 0
	global_store_dwordx4 v248, v[52:55], s[100:101]
	global_store_dwordx4 v248, v[60:63], s[100:101] offset:512
	s_add_u32 s100, s40, 0x110000
	s_addc_u32 s101, s41, 0
	global_store_dwordx4 v248, v[48:51], s[100:101]
	global_store_dwordx4 v248, v[56:59], s[100:101] offset:512
	s_add_u32 s100, s40, 0x120000
	s_addc_u32 s101, s41, 0
	global_store_dwordx4 v248, v[36:39], s[100:101]
	global_store_dwordx4 v248, v[44:47], s[100:101] offset:512
	s_add_u32 s100, s40, 0x130000
	s_addc_u32 s101, s41, 0
	global_store_dwordx4 v248, v[32:35], s[100:101]
	global_store_dwordx4 v248, v[40:43], s[100:101] offset:512
	s_waitcnt vmcnt(16)
	v_pk_add_f32 v[20:21], v[20:21], v[216:217]
	v_pk_add_f32 v[22:23], v[22:23], v[218:219]
	v_pk_add_f32 v[16:17], v[16:17], v[220:221]
	v_pk_add_f32 v[18:19], v[18:19], v[222:223]
	v_pk_add_f32 v[28:29], v[28:29], v[224:225]
	v_pk_add_f32 v[30:31], v[30:31], v[226:227]
	v_pk_add_f32 v[24:25], v[24:25], v[228:229]
	v_pk_add_f32 v[26:27], v[26:27], v[230:231]
	v_pk_add_f32 v[12:13], v[12:13], v[232:233]
	v_pk_add_f32 v[14:15], v[14:15], v[234:235]
	v_pk_add_f32 v[8:9], v[8:9], v[236:237]
	v_pk_add_f32 v[10:11], v[10:11], v[238:239]
	v_pk_add_f32 v[4:5], v[4:5], v[240:241]
	v_pk_add_f32 v[6:7], v[6:7], v[242:243]
	v_pk_add_f32 v[0:1], v[0:1], v[244:245]
	v_pk_add_f32 v[2:3], v[2:3], v[246:247]
	s_add_u32 s100, s40, 0x140000
	s_addc_u32 s101, s41, 0
	global_store_dwordx4 v248, v[20:23], s[100:101]
	global_store_dwordx4 v248, v[28:31], s[100:101] offset:512
	s_add_u32 s100, s40, 0x150000
	s_addc_u32 s101, s41, 0
	global_store_dwordx4 v248, v[16:19], s[100:101]
	global_store_dwordx4 v248, v[24:27], s[100:101] offset:512
	s_add_u32 s100, s40, 0x160000
	s_addc_u32 s101, s41, 0
	global_store_dwordx4 v248, v[12:15], s[100:101]
	global_store_dwordx4 v248, v[4:7], s[100:101] offset:512
	s_add_u32 s100, s40, 0x170000
	s_addc_u32 s101, s41, 0
	global_store_dwordx4 v248, v[8:11], s[100:101]
	global_store_dwordx4 v248, v[0:3], s[100:101] offset:512
	v_readlane_b32 s0, v250, 32
	s_add_i32 s50, s50, s0
	s_cmpk_gt_i32 s50, 0xff
	s_cbranch_scc1 .LBB0_1013

.LBB0_1016:
	v_add_u32_e32 v32, s39, v40
	v_ashrrev_i32_e32 v33, 31, v32
	v_lshlrev_b64 v[32:33], 12, v[32:33]
	v_lshl_add_u64 v[48:49], v[36:37], 0, v[32:33]
	s_nop 0
	v_readfirstlane_b32 s100, v48
	v_readfirstlane_b32 s101, v49
	v_and_b32_e32 v132, 63, v171
	v_lshrrev_b32_e32 v133, 5, v132
	v_and_b32_e32 v134, 31, v132
	v_and_b32_e32 v135, 15, v132
	v_lshrrev_b32_e32 v136, 4, v132
	v_lshrrev_b32_e32 v137, 6, v171
	v_lshlrev_b32_e32 v137, 13, v137
	v_add_u32_e32 v137, 0x2000, v137
	s_nop 1
	v_readfirstlane_b32 s99, v137
	v_lshl_add_u32 v137, v135, 9, v137
	v_add_u32_e32 v138, 0, v133
	v_xor_b32_e32 v139, v134, v138
	v_mul_u32_u24_e32 v138, 0x1000, v138
	v_lshl_add_u32 v140, v139, 4, v138
	v_add_u32_e32 v138, 2, v133
	v_xor_b32_e32 v139, v134, v138
	v_mul_u32_u24_e32 v138, 0x1000, v138
	v_lshl_add_u32 v141, v139, 4, v138
	v_add_u32_e32 v138, 4, v133
	v_xor_b32_e32 v139, v134, v138
	v_mul_u32_u24_e32 v138, 0x1000, v138
	v_lshl_add_u32 v142, v139, 4, v138
	v_add_u32_e32 v138, 6, v133
	v_xor_b32_e32 v139, v134, v138
	v_mul_u32_u24_e32 v138, 0x1000, v138
	v_lshl_add_u32 v143, v139, 4, v138
	v_add_u32_e32 v138, 8, v133
	v_xor_b32_e32 v139, v134, v138
	v_mul_u32_u24_e32 v138, 0x1000, v138
	v_lshl_add_u32 v144, v139, 4, v138
	v_add_u32_e32 v138, 10, v133
	v_xor_b32_e32 v139, v134, v138
	v_mul_u32_u24_e32 v138, 0x1000, v138
	v_lshl_add_u32 v145, v139, 4, v138
	v_add_u32_e32 v138, 12, v133
	v_xor_b32_e32 v139, v134, v138
	v_mul_u32_u24_e32 v138, 0x1000, v138
	v_lshl_add_u32 v146, v139, 4, v138
	v_add_u32_e32 v138, 14, v133
	v_xor_b32_e32 v139, v134, v138
	v_mul_u32_u24_e32 v138, 0x1000, v138
	v_lshl_add_u32 v147, v139, 4, v138
	v_add_u32_e32 v138, 0, v136
	v_xor_b32_e32 v138, v138, v135
	v_lshl_add_u32 v148, v138, 4, v137
	v_add_u32_e32 v138, 4, v136
	v_xor_b32_e32 v138, v138, v135
	v_lshl_add_u32 v149, v138, 4, v137
	v_add_u32_e32 v138, 8, v136
	v_xor_b32_e32 v138, v138, v135
	v_lshl_add_u32 v150, v138, 4, v137
	v_add_u32_e32 v138, 12, v136
	v_xor_b32_e32 v138, v138, v135
	v_lshl_add_u32 v151, v138, 4, v137
	v_add_u32_e32 v138, 16, v136
	v_xor_b32_e32 v138, v138, v135
	v_lshl_add_u32 v152, v138, 4, v137
	v_add_u32_e32 v138, 20, v136
	v_xor_b32_e32 v138, v138, v135
	v_lshl_add_u32 v153, v138, 4, v137
	v_add_u32_e32 v138, 24, v136
	v_xor_b32_e32 v138, v138, v135
	v_lshl_add_u32 v154, v138, 4, v137
	v_add_u32_e32 v138, 28, v136
	v_xor_b32_e32 v138, v138, v135
	v_lshl_add_u32 v155, v138, 4, v137
	s_mov_b32 m0, s99
	s_nop 0
	global_load_lds_dwordx4 v140, s[100:101]
	s_add_u32 s99, s99, 0x400
	s_mov_b32 m0, s99
	s_nop 0
	global_load_lds_dwordx4 v141, s[100:101]
	s_add_u32 s99, s99, 0x400
	s_mov_b32 m0, s99
	s_nop 0
	global_load_lds_dwordx4 v142, s[100:101]
	s_add_u32 s99, s99, 0x400
	s_mov_b32 m0, s99
	s_nop 0
	global_load_lds_dwordx4 v143, s[100:101]
	s_add_u32 s99, s99, 0x400
	s_mov_b32 m0, s99
	s_nop 0
	global_load_lds_dwordx4 v144, s[100:101]
	s_add_u32 s99, s99, 0x400
	s_mov_b32 m0, s99
	s_nop 0
	global_load_lds_dwordx4 v145, s[100:101]
	s_add_u32 s99, s99, 0x400
	s_mov_b32 m0, s99
	s_nop 0
	global_load_lds_dwordx4 v146, s[100:101]
	s_add_u32 s99, s99, 0x400
	s_mov_b32 m0, s99
	s_nop 0
	global_load_lds_dwordx4 v147, s[100:101]
	s_waitcnt vmcnt(0)
	ds_read_b128 v[100:103], v148
	ds_read_b128 v[104:107], v149
	ds_read_b128 v[108:111], v150
	ds_read_b128 v[112:115], v151
	ds_read_b128 v[116:119], v152
	ds_read_b128 v[120:123], v153
	ds_read_b128 v[124:127], v154
	ds_read_b128 v[128:131], v155
	s_waitcnt lgkmcnt(7)
	v_mfma_f32_16x16x32_bf16 v[32:35], v[100:103], v[24:27], 0
	s_waitcnt lgkmcnt(6)
	v_mfma_f32_16x16x32_bf16 v[32:35], v[104:107], v[0:3], v[32:35]
	s_waitcnt lgkmcnt(5)
	v_mfma_f32_16x16x32_bf16 v[32:35], v[108:111], v[4:7], v[32:35]
	s_waitcnt lgkmcnt(4)
	v_mfma_f32_16x16x32_bf16 v[32:35], v[112:115], v[8:11], v[32:35]
	s_waitcnt lgkmcnt(3)
	v_mfma_f32_16x16x32_bf16 v[32:35], v[116:119], v[12:15], v[32:35]
	s_waitcnt lgkmcnt(2)
	v_mfma_f32_16x16x32_bf16 v[32:35], v[120:123], v[16:19], v[32:35]
	s_waitcnt lgkmcnt(1)
	v_mfma_f32_16x16x32_bf16 v[32:35], v[124:127], v[20:23], v[32:35]
	s_waitcnt lgkmcnt(0)
	v_mfma_f32_16x16x32_bf16 v[32:35], v[128:131], v[28:31], v[32:35]
	s_nop 7
	ds_write_b128 v41, v[32:35]
	s_waitcnt lgkmcnt(0)
	s_barrier
	s_and_saveexec_b64 s[0:1], vcc
	s_cbranch_execz .LBB0_1015
	ds_read_b128 v[44:47], v41 offset:1024
	s_waitcnt lgkmcnt(0)
	v_pk_add_f32 v[46:47], v[34:35], v[46:47]
	v_pk_add_f32 v[44:45], v[32:33], v[44:45]
	ds_read_b128 v[32:35], v41 offset:2048
	s_waitcnt lgkmcnt(0)
	v_pk_add_f32 v[46:47], v[46:47], v[34:35]
	v_pk_add_f32 v[44:45], v[44:45], v[32:33]
	ds_read_b128 v[32:35], v41 offset:3072
	s_waitcnt lgkmcnt(0)
	v_pk_add_f32 v[46:47], v[46:47], v[34:35]
	v_pk_add_f32 v[44:45], v[44:45], v[32:33]
	ds_read_b128 v[32:35], v41 offset:4096
	s_waitcnt lgkmcnt(0)
	v_pk_add_f32 v[46:47], v[46:47], v[34:35]
	v_pk_add_f32 v[44:45], v[44:45], v[32:33]
	ds_read_b128 v[32:35], v41 offset:5120
	s_waitcnt lgkmcnt(0)
	v_pk_add_f32 v[46:47], v[46:47], v[34:35]
	v_pk_add_f32 v[44:45], v[44:45], v[32:33]
	ds_read_b128 v[32:35], v41 offset:6144
	s_waitcnt lgkmcnt(0)
	v_pk_add_f32 v[46:47], v[46:47], v[34:35]
	v_pk_add_f32 v[44:45], v[44:45], v[32:33]
	ds_read_b128 v[32:35], v41 offset:7168
	s_waitcnt lgkmcnt(0)
	v_pk_add_f32 v[44:45], v[44:45], v[32:33]
	v_add_u32_e32 v32, s39, v42
	v_ashrrev_i32_e32 v33, 31, v32
	v_lshl_add_u64 v[48:49], v[32:33], 2, v[38:39]
	v_pk_add_f32 v[46:47], v[46:47], v[34:35]
	global_load_dwordx4 v[32:35], v[48:49], off
	s_waitcnt vmcnt(0)
	v_pk_add_f32 v[34:35], v[46:47], v[34:35]
	v_pk_add_f32 v[32:33], v[44:45], v[32:33]
	global_store_dwordx4 v[48:49], v[32:35], off
	s_branch .LBB0_1015

.LBB0_1137:
	v_add_u32_e32 v32, s38, v40
	v_ashrrev_i32_e32 v33, 31, v32
	v_lshlrev_b64 v[32:33], 12, v[32:33]
	v_lshl_add_u64 v[48:49], v[36:37], 0, v[32:33]
	s_nop 0
	v_readfirstlane_b32 s100, v48
	v_readfirstlane_b32 s101, v49
	v_and_b32_e32 v132, 63, v171
	v_lshrrev_b32_e32 v133, 5, v132
	v_and_b32_e32 v134, 31, v132
	v_and_b32_e32 v135, 15, v132
	v_lshrrev_b32_e32 v136, 4, v132
	v_lshrrev_b32_e32 v137, 6, v171
	v_lshlrev_b32_e32 v137, 13, v137
	v_add_u32_e32 v137, 0x2000, v137
	s_nop 1
	v_readfirstlane_b32 s99, v137
	v_lshl_add_u32 v137, v135, 9, v137
	v_add_u32_e32 v138, 0, v133
	v_xor_b32_e32 v139, v134, v138
	v_mul_u32_u24_e32 v138, 0x1000, v138
	v_lshl_add_u32 v140, v139, 4, v138
	v_add_u32_e32 v138, 2, v133
	v_xor_b32_e32 v139, v134, v138
	v_mul_u32_u24_e32 v138, 0x1000, v138
	v_lshl_add_u32 v141, v139, 4, v138
	v_add_u32_e32 v138, 4, v133
	v_xor_b32_e32 v139, v134, v138
	v_mul_u32_u24_e32 v138, 0x1000, v138
	v_lshl_add_u32 v142, v139, 4, v138
	v_add_u32_e32 v138, 6, v133
	v_xor_b32_e32 v139, v134, v138
	v_mul_u32_u24_e32 v138, 0x1000, v138
	v_lshl_add_u32 v143, v139, 4, v138
	v_add_u32_e32 v138, 8, v133
	v_xor_b32_e32 v139, v134, v138
	v_mul_u32_u24_e32 v138, 0x1000, v138
	v_lshl_add_u32 v144, v139, 4, v138
	v_add_u32_e32 v138, 10, v133
	v_xor_b32_e32 v139, v134, v138
	v_mul_u32_u24_e32 v138, 0x1000, v138
	v_lshl_add_u32 v145, v139, 4, v138
	v_add_u32_e32 v138, 12, v133
	v_xor_b32_e32 v139, v134, v138
	v_mul_u32_u24_e32 v138, 0x1000, v138
	v_lshl_add_u32 v146, v139, 4, v138
	v_add_u32_e32 v138, 14, v133
	v_xor_b32_e32 v139, v134, v138
	v_mul_u32_u24_e32 v138, 0x1000, v138
	v_lshl_add_u32 v147, v139, 4, v138
	v_add_u32_e32 v138, 0, v136
	v_xor_b32_e32 v138, v138, v135
	v_lshl_add_u32 v148, v138, 4, v137
	v_add_u32_e32 v138, 4, v136
	v_xor_b32_e32 v138, v138, v135
	v_lshl_add_u32 v149, v138, 4, v137
	v_add_u32_e32 v138, 8, v136
	v_xor_b32_e32 v138, v138, v135
	v_lshl_add_u32 v150, v138, 4, v137
	v_add_u32_e32 v138, 12, v136
	v_xor_b32_e32 v138, v138, v135
	v_lshl_add_u32 v151, v138, 4, v137
	v_add_u32_e32 v138, 16, v136
	v_xor_b32_e32 v138, v138, v135
	v_lshl_add_u32 v152, v138, 4, v137
	v_add_u32_e32 v138, 20, v136
	v_xor_b32_e32 v138, v138, v135
	v_lshl_add_u32 v153, v138, 4, v137
	v_add_u32_e32 v138, 24, v136
	v_xor_b32_e32 v138, v138, v135
	v_lshl_add_u32 v154, v138, 4, v137
	v_add_u32_e32 v138, 28, v136
	v_xor_b32_e32 v138, v138, v135
	v_lshl_add_u32 v155, v138, 4, v137
	s_mov_b32 m0, s99
	s_nop 0
	global_load_lds_dwordx4 v140, s[100:101]
	s_add_u32 s99, s99, 0x400
	s_mov_b32 m0, s99
	s_nop 0
	global_load_lds_dwordx4 v141, s[100:101]
	s_add_u32 s99, s99, 0x400
	s_mov_b32 m0, s99
	s_nop 0
	global_load_lds_dwordx4 v142, s[100:101]
	s_add_u32 s99, s99, 0x400
	s_mov_b32 m0, s99
	s_nop 0
	global_load_lds_dwordx4 v143, s[100:101]
	s_add_u32 s99, s99, 0x400
	s_mov_b32 m0, s99
	s_nop 0
	global_load_lds_dwordx4 v144, s[100:101]
	s_add_u32 s99, s99, 0x400
	s_mov_b32 m0, s99
	s_nop 0
	global_load_lds_dwordx4 v145, s[100:101]
	s_add_u32 s99, s99, 0x400
	s_mov_b32 m0, s99
	s_nop 0
	global_load_lds_dwordx4 v146, s[100:101]
	s_add_u32 s99, s99, 0x400
	s_mov_b32 m0, s99
	s_nop 0
	global_load_lds_dwordx4 v147, s[100:101]
	s_waitcnt vmcnt(0)
	ds_read_b128 v[100:103], v148
	ds_read_b128 v[104:107], v149
	ds_read_b128 v[108:111], v150
	ds_read_b128 v[112:115], v151
	ds_read_b128 v[116:119], v152
	ds_read_b128 v[120:123], v153
	ds_read_b128 v[124:127], v154
	ds_read_b128 v[128:131], v155
	s_waitcnt lgkmcnt(7)
	v_mfma_f32_16x16x32_bf16 v[32:35], v[100:103], v[24:27], 0
	s_waitcnt lgkmcnt(6)
	v_mfma_f32_16x16x32_bf16 v[32:35], v[104:107], v[0:3], v[32:35]
	s_waitcnt lgkmcnt(5)
	v_mfma_f32_16x16x32_bf16 v[32:35], v[108:111], v[4:7], v[32:35]
	s_waitcnt lgkmcnt(4)
	v_mfma_f32_16x16x32_bf16 v[32:35], v[112:115], v[8:11], v[32:35]
	s_waitcnt lgkmcnt(3)
	v_mfma_f32_16x16x32_bf16 v[32:35], v[116:119], v[12:15], v[32:35]
	s_waitcnt lgkmcnt(2)
	v_mfma_f32_16x16x32_bf16 v[32:35], v[120:123], v[16:19], v[32:35]
	s_waitcnt lgkmcnt(1)
	v_mfma_f32_16x16x32_bf16 v[32:35], v[124:127], v[20:23], v[32:35]
	s_waitcnt lgkmcnt(0)
	v_mfma_f32_16x16x32_bf16 v[32:35], v[128:131], v[28:31], v[32:35]
	s_nop 7
	ds_write_b128 v41, v[32:35]
	s_waitcnt lgkmcnt(0)
	s_barrier
	s_and_saveexec_b64 s[0:1], vcc
	s_cbranch_execz .LBB0_1136
	ds_read_b128 v[44:47], v41 offset:1024
	s_waitcnt lgkmcnt(0)
	v_pk_add_f32 v[46:47], v[34:35], v[46:47]
	v_pk_add_f32 v[44:45], v[32:33], v[44:45]
	ds_read_b128 v[32:35], v41 offset:2048
	s_waitcnt lgkmcnt(0)
	v_pk_add_f32 v[46:47], v[46:47], v[34:35]
	v_pk_add_f32 v[44:45], v[44:45], v[32:33]
	ds_read_b128 v[32:35], v41 offset:3072
	s_waitcnt lgkmcnt(0)
	v_pk_add_f32 v[46:47], v[46:47], v[34:35]
	v_pk_add_f32 v[44:45], v[44:45], v[32:33]
	ds_read_b128 v[32:35], v41 offset:4096
	s_waitcnt lgkmcnt(0)
	v_pk_add_f32 v[46:47], v[46:47], v[34:35]
	v_pk_add_f32 v[44:45], v[44:45], v[32:33]
	ds_read_b128 v[32:35], v41 offset:5120
	s_waitcnt lgkmcnt(0)
	v_pk_add_f32 v[46:47], v[46:47], v[34:35]
	v_pk_add_f32 v[44:45], v[44:45], v[32:33]
	ds_read_b128 v[32:35], v41 offset:6144
	s_waitcnt lgkmcnt(0)
	v_pk_add_f32 v[46:47], v[46:47], v[34:35]
	v_pk_add_f32 v[44:45], v[44:45], v[32:33]
	ds_read_b128 v[32:35], v41 offset:7168
	s_waitcnt lgkmcnt(0)
	v_pk_add_f32 v[34:35], v[46:47], v[34:35]
	v_pk_add_f32 v[32:33], v[44:45], v[32:33]
	v_add_u32_e32 v44, s38, v42
	v_max_f32_e32 v32, 0, v32
	v_max_f32_e32 v33, 0, v33
	v_max_f32_e32 v34, 0, v34
	v_max_f32_e32 v35, 0, v35
	v_pk_mul_f32 v[32:33], v[32:33], v[32:33]
	v_pk_mul_f32 v[34:35], v[34:35], v[34:35]
	v_ashrrev_i32_e32 v45, 31, v44
	v_cvt_pk_bf16_f32 v32, v32, v33
	v_cvt_pk_bf16_f32 v33, v34, v35
	v_lshl_add_u64 v[34:35], v[44:45], 1, v[38:39]
	global_store_dwordx2 v[34:35], v[32:33], off
	s_branch .LBB0_1136

.LBB0_1194:
	s_or_b64 exec, exec, s[42:43]
	v_or_b32_e32 v128, s36, v141
	v_add_u32_e32 v130, v128, v142
	v_lshlrev_b32_e32 v128, 5, v139
	v_lshlrev_b32_e32 v129, 3, v140
	v_or3_b32 v128, v128, v129, s0
	v_ashrrev_i32_e32 v131, 31, v130
	v_lshlrev_b64 v[132:133], 13, v[130:131]
	v_ashrrev_i32_e32 v129, 31, v128
	v_lshl_add_u64 v[132:133], s[40:41], 0, v[132:133]
	v_lshlrev_b64 v[128:129], 2, v[128:129]
	v_lshl_add_u64 v[140:141], v[132:133], 0, v[128:129]
	v_and_b32_e32 v249, 63, v171
	v_and_b32_e32 v146, 15, v249
	v_lshrrev_b32_e32 v147, 4, v249
	v_lshrrev_b32_e32 v164, 6, v171
	v_mul_u32_u24_e32 v164, 0xe00, v164
	v_add_u32_e32 v164, 0x20000, v164
	v_mul_u32_u24_e32 v165, 0x90, v146
	v_lshl_add_u32 v165, v147, 5, v165
	v_add_u32_e32 v165, v165, v164
	v_lshrrev_b32_e32 v166, 3, v249
	v_mul_u32_u24_e32 v167, 0x90, v166
	v_and_b32_e32 v148, 7, v249
	v_lshl_add_u32 v167, v148, 4, v167
	v_add_u32_e32 v167, v167, v164
	v_sub_u32_e32 v248, v130, v146
	v_add_u32_e32 v248, v248, v166
	v_lshlrev_b32_e32 v248, 13, v248
	v_lshlrev_b32_e32 v149, 5, v147
	v_sub_u32_e32 v149, v128, v149
	v_lshl_add_u32 v149, v148, 4, v149
	v_add_u32_e32 v248, v248, v149
	s_mov_b64 s[100:101], s[40:41]
	global_load_dwordx4 v[184:187], v248, s[100:101]
	global_load_dwordx4 v[192:195], v248, s[100:101] offset:512
	s_add_u32 s100, s40, 0x10000
	s_addc_u32 s101, s41, 0
	global_load_dwordx4 v[188:191], v248, s[100:101]
	global_load_dwordx4 v[196:199], v248, s[100:101] offset:512
	s_add_u32 s100, s40, 0x20000
	s_addc_u32 s101, s41, 0
	global_load_dwordx4 v[200:203], v248, s[100:101]
	global_load_dwordx4 v[208:211], v248, s[100:101] offset:512
	s_add_u32 s100, s40, 0x30000
	s_addc_u32 s101, s41, 0
	global_load_dwordx4 v[204:207], v248, s[100:101]
	global_load_dwordx4 v[212:215], v248, s[100:101] offset:512
	s_add_u32 s100, s40, 0x40000
	s_addc_u32 s101, s41, 0
	global_load_dwordx4 v[216:219], v248, s[100:101]
	global_load_dwordx4 v[224:227], v248, s[100:101] offset:512
	s_add_u32 s100, s40, 0x50000
	s_addc_u32 s101, s41, 0
	global_load_dwordx4 v[220:223], v248, s[100:101]
	global_load_dwordx4 v[228:231], v248, s[100:101] offset:512
	s_add_u32 s100, s40, 0x60000
	s_addc_u32 s101, s41, 0
	global_load_dwordx4 v[232:235], v248, s[100:101]
	global_load_dwordx4 v[240:243], v248, s[100:101] offset:512
	s_add_u32 s100, s40, 0x70000
	s_addc_u32 s101, s41, 0
	global_load_dwordx4 v[236:239], v248, s[100:101]
	global_load_dwordx4 v[244:247], v248, s[100:101] offset:512
	ds_write_b128 v165, v[124:127]
	ds_write_b128 v165, v[120:123] offset:16
	ds_read_b128 v[124:127], v167
	ds_read_b128 v[120:123], v167 offset:1152
	ds_write_b128 v165, v[116:119]
	ds_write_b128 v165, v[112:115] offset:16
	ds_read_b128 v[116:119], v167
	ds_read_b128 v[112:115], v167 offset:1152
	ds_write_b128 v165, v[100:103]
	ds_write_b128 v165, v[96:99] offset:16
	ds_read_b128 v[100:103], v167
	ds_read_b128 v[96:99], v167 offset:1152
	ds_write_b128 v165, v[108:111]
	ds_write_b128 v165, v[104:107] offset:16
	ds_read_b128 v[108:111], v167
	ds_read_b128 v[104:107], v167 offset:1152
	ds_write_b128 v165, v[84:87]
	ds_write_b128 v165, v[80:83] offset:16
	ds_read_b128 v[84:87], v167
	ds_read_b128 v[80:83], v167 offset:1152
	ds_write_b128 v165, v[92:95]
	ds_write_b128 v165, v[88:91] offset:16
	ds_read_b128 v[92:95], v167
	ds_read_b128 v[88:91], v167 offset:1152
	ds_write_b128 v165, v[68:71]
	ds_write_b128 v165, v[64:67] offset:16
	ds_read_b128 v[68:71], v167
	ds_read_b128 v[64:67], v167 offset:1152
	ds_write_b128 v165, v[76:79]
	ds_write_b128 v165, v[72:75] offset:16
	ds_read_b128 v[76:79], v167
	ds_read_b128 v[72:75], v167 offset:1152
	ds_write_b128 v165, v[52:55]
	ds_write_b128 v165, v[48:51] offset:16
	ds_read_b128 v[52:55], v167
	ds_read_b128 v[48:51], v167 offset:1152
	ds_write_b128 v165, v[60:63]
	ds_write_b128 v165, v[56:59] offset:16
	ds_read_b128 v[60:63], v167
	ds_read_b128 v[56:59], v167 offset:1152
	ds_write_b128 v165, v[36:39]
	ds_write_b128 v165, v[32:35] offset:16
	ds_read_b128 v[36:39], v167
	ds_read_b128 v[32:35], v167 offset:1152
	ds_write_b128 v165, v[44:47]
	ds_write_b128 v165, v[40:43] offset:16
	ds_read_b128 v[44:47], v167
	ds_read_b128 v[40:43], v167 offset:1152
	ds_write_b128 v165, v[20:23]
	ds_write_b128 v165, v[16:19] offset:16
	ds_read_b128 v[20:23], v167
	ds_read_b128 v[16:19], v167 offset:1152
	ds_write_b128 v165, v[28:31]
	ds_write_b128 v165, v[24:27] offset:16
	ds_read_b128 v[28:31], v167
	ds_read_b128 v[24:27], v167 offset:1152
	ds_write_b128 v165, v[12:15]
	ds_write_b128 v165, v[8:11] offset:16
	ds_read_b128 v[12:15], v167
	ds_read_b128 v[8:11], v167 offset:1152
	ds_write_b128 v165, v[4:7]
	ds_write_b128 v165, v[0:3] offset:16
	ds_read_b128 v[4:7], v167
	ds_read_b128 v[0:3], v167 offset:1152
	s_waitcnt lgkmcnt(0)
	s_waitcnt vmcnt(8)
	v_pk_add_f32 v[124:125], v[124:125], v[184:185]
	v_pk_add_f32 v[126:127], v[126:127], v[186:187]
	v_pk_add_f32 v[120:121], v[120:121], v[188:189]
	v_pk_add_f32 v[122:123], v[122:123], v[190:191]
	v_pk_add_f32 v[116:117], v[116:117], v[192:193]
	v_pk_add_f32 v[118:119], v[118:119], v[194:195]
	v_pk_add_f32 v[112:113], v[112:113], v[196:197]
	v_pk_add_f32 v[114:115], v[114:115], v[198:199]
	v_pk_add_f32 v[100:101], v[100:101], v[200:201]
	v_pk_add_f32 v[102:103], v[102:103], v[202:203]
	v_pk_add_f32 v[96:97], v[96:97], v[204:205]
	v_pk_add_f32 v[98:99], v[98:99], v[206:207]
	v_pk_add_f32 v[108:109], v[108:109], v[208:209]
	v_pk_add_f32 v[110:111], v[110:111], v[210:211]
	v_pk_add_f32 v[104:105], v[104:105], v[212:213]
	v_pk_add_f32 v[106:107], v[106:107], v[214:215]
	s_add_u32 s100, s40, 0x100000
	s_addc_u32 s101, s41, 0
	global_load_dwordx4 v[184:187], v248, s[100:101]
	global_load_dwordx4 v[192:195], v248, s[100:101] offset:512
	s_add_u32 s100, s40, 0x110000
	s_addc_u32 s101, s41, 0
	global_load_dwordx4 v[188:191], v248, s[100:101]
	global_load_dwordx4 v[196:199], v248, s[100:101] offset:512
	s_add_u32 s100, s40, 0x120000
	s_addc_u32 s101, s41, 0
	global_load_dwordx4 v[200:203], v248, s[100:101]
	global_load_dwordx4 v[208:211], v248, s[100:101] offset:512
	s_add_u32 s100, s40, 0x130000
	s_addc_u32 s101, s41, 0
	global_load_dwordx4 v[204:207], v248, s[100:101]
	global_load_dwordx4 v[212:215], v248, s[100:101] offset:512
	s_mov_b64 s[100:101], s[40:41]
	global_store_dwordx4 v248, v[124:127], s[100:101]
	global_store_dwordx4 v248, v[116:119], s[100:101] offset:512
	s_add_u32 s100, s40, 0x10000
	s_addc_u32 s101, s41, 0
	global_store_dwordx4 v248, v[120:123], s[100:101]
	global_store_dwordx4 v248, v[112:115], s[100:101] offset:512
	s_add_u32 s100, s40, 0x20000
	s_addc_u32 s101, s41, 0
	global_store_dwordx4 v248, v[100:103], s[100:101]
	global_store_dwordx4 v248, v[108:111], s[100:101] offset:512
	s_add_u32 s100, s40, 0x30000
	s_addc_u32 s101, s41, 0
	global_store_dwordx4 v248, v[96:99], s[100:101]
	global_store_dwordx4 v248, v[104:107], s[100:101] offset:512
	s_waitcnt vmcnt(16)
	v_pk_add_f32 v[84:85], v[84:85], v[216:217]
	v_pk_add_f32 v[86:87], v[86:87], v[218:219]
	v_pk_add_f32 v[80:81], v[80:81], v[220:221]
	v_pk_add_f32 v[82:83], v[82:83], v[222:223]
	v_pk_add_f32 v[92:93], v[92:93], v[224:225]
	v_pk_add_f32 v[94:95], v[94:95], v[226:227]
	v_pk_add_f32 v[88:89], v[88:89], v[228:229]
	v_pk_add_f32 v[90:91], v[90:91], v[230:231]
	v_pk_add_f32 v[68:69], v[68:69], v[232:233]
	v_pk_add_f32 v[70:71], v[70:71], v[234:235]
	v_pk_add_f32 v[64:65], v[64:65], v[236:237]
	v_pk_add_f32 v[66:67], v[66:67], v[238:239]
	v_pk_add_f32 v[76:77], v[76:77], v[240:241]
	v_pk_add_f32 v[78:79], v[78:79], v[242:243]
	v_pk_add_f32 v[72:73], v[72:73], v[244:245]
	v_pk_add_f32 v[74:75], v[74:75], v[246:247]
	s_add_u32 s100, s40, 0x140000
	s_addc_u32 s101, s41, 0
	global_load_dwordx4 v[216:219], v248, s[100:101]
	global_load_dwordx4 v[224:227], v248, s[100:101] offset:512
	s_add_u32 s100, s40, 0x150000
	s_addc_u32 s101, s41, 0
	global_load_dwordx4 v[220:223], v248, s[100:101]
	global_load_dwordx4 v[228:231], v248, s[100:101] offset:512
	s_add_u32 s100, s40, 0x160000
	s_addc_u32 s101, s41, 0
	global_load_dwordx4 v[232:235], v248, s[100:101]
	global_load_dwordx4 v[240:243], v248, s[100:101] offset:512
	s_add_u32 s100, s40, 0x170000
	s_addc_u32 s101, s41, 0
	global_load_dwordx4 v[236:239], v248, s[100:101]
	global_load_dwordx4 v[244:247], v248, s[100:101] offset:512
	s_add_u32 s100, s40, 0x40000
	s_addc_u32 s101, s41, 0
	global_store_dwordx4 v248, v[84:87], s[100:101]
	global_store_dwordx4 v248, v[92:95], s[100:101] offset:512
	s_add_u32 s100, s40, 0x50000
	s_addc_u32 s101, s41, 0
	global_store_dwordx4 v248, v[80:83], s[100:101]
	global_store_dwordx4 v248, v[88:91], s[100:101] offset:512
	s_add_u32 s100, s40, 0x60000
	s_addc_u32 s101, s41, 0
	global_store_dwordx4 v248, v[68:71], s[100:101]
	global_store_dwordx4 v248, v[76:79], s[100:101] offset:512
	s_add_u32 s100, s40, 0x70000
	s_addc_u32 s101, s41, 0
	global_store_dwordx4 v248, v[64:67], s[100:101]
	global_store_dwordx4 v248, v[72:75], s[100:101] offset:512
	s_waitcnt vmcnt(24)
	v_pk_add_f32 v[52:53], v[52:53], v[184:185]
	v_pk_add_f32 v[54:55], v[54:55], v[186:187]
	v_pk_add_f32 v[48:49], v[48:49], v[188:189]
	v_pk_add_f32 v[50:51], v[50:51], v[190:191]
	v_pk_add_f32 v[60:61], v[60:61], v[192:193]
	v_pk_add_f32 v[62:63], v[62:63], v[194:195]
	v_pk_add_f32 v[56:57], v[56:57], v[196:197]
	v_pk_add_f32 v[58:59], v[58:59], v[198:199]
	v_pk_add_f32 v[36:37], v[36:37], v[200:201]
	v_pk_add_f32 v[38:39], v[38:39], v[202:203]
	v_pk_add_f32 v[32:33], v[32:33], v[204:205]
	v_pk_add_f32 v[34:35], v[34:35], v[206:207]
	v_pk_add_f32 v[44:45], v[44:45], v[208:209]
	v_pk_add_f32 v[46:47], v[46:47], v[210:211]
	v_pk_add_f32 v[40:41], v[40:41], v[212:213]
	v_pk_add_f32 v[42:43], v[42:43], v[214:215]
	s_add_u32 s100, s40, 0x100000
	s_addc_u32 s101, s41, 0
	global_store_dwordx4 v248, v[52:55], s[100:101]
	global_store_dwordx4 v248, v[60:63], s[100:101] offset:512
	s_add_u32 s100, s40, 0x110000
	s_addc_u32 s101, s41, 0
	global_store_dwordx4 v248, v[48:51], s[100:101]
	global_store_dwordx4 v248, v[56:59], s[100:101] offset:512
	s_add_u32 s100, s40, 0x120000
	s_addc_u32 s101, s41, 0
	global_store_dwordx4 v248, v[36:39], s[100:101]
	global_store_dwordx4 v248, v[44:47], s[100:101] offset:512
	s_add_u32 s100, s40, 0x130000
	s_addc_u32 s101, s41, 0
	global_store_dwordx4 v248, v[32:35], s[100:101]
	global_store_dwordx4 v248, v[40:43], s[100:101] offset:512
	s_waitcnt vmcnt(16)
	v_pk_add_f32 v[20:21], v[20:21], v[216:217]
	v_pk_add_f32 v[22:23], v[22:23], v[218:219]
	v_pk_add_f32 v[16:17], v[16:17], v[220:221]
	v_pk_add_f32 v[18:19], v[18:19], v[222:223]
	v_pk_add_f32 v[28:29], v[28:29], v[224:225]
	v_pk_add_f32 v[30:31], v[30:31], v[226:227]
	v_pk_add_f32 v[24:25], v[24:25], v[228:229]
	v_pk_add_f32 v[26:27], v[26:27], v[230:231]
	v_pk_add_f32 v[12:13], v[12:13], v[232:233]
	v_pk_add_f32 v[14:15], v[14:15], v[234:235]
	v_pk_add_f32 v[8:9], v[8:9], v[236:237]
	v_pk_add_f32 v[10:11], v[10:11], v[238:239]
	v_pk_add_f32 v[4:5], v[4:5], v[240:241]
	v_pk_add_f32 v[6:7], v[6:7], v[242:243]
	v_pk_add_f32 v[0:1], v[0:1], v[244:245]
	v_pk_add_f32 v[2:3], v[2:3], v[246:247]
	s_add_u32 s100, s40, 0x140000
	s_addc_u32 s101, s41, 0
	global_store_dwordx4 v248, v[20:23], s[100:101]
	global_store_dwordx4 v248, v[28:31], s[100:101] offset:512
	s_add_u32 s100, s40, 0x150000
	s_addc_u32 s101, s41, 0
	global_store_dwordx4 v248, v[16:19], s[100:101]
	global_store_dwordx4 v248, v[24:27], s[100:101] offset:512
	s_add_u32 s100, s40, 0x160000
	s_addc_u32 s101, s41, 0
	global_store_dwordx4 v248, v[12:15], s[100:101]
	global_store_dwordx4 v248, v[4:7], s[100:101] offset:512
	s_add_u32 s100, s40, 0x170000
	s_addc_u32 s101, s41, 0
	global_store_dwordx4 v248, v[8:11], s[100:101]
	global_store_dwordx4 v248, v[0:3], s[100:101] offset:512
	v_readlane_b32 s0, v250, 32
	s_add_i32 s4, s8, s0
	s_cmpk_gt_i32 s4, 0xff
	s_cbranch_scc1 .LBB0_1201
